# hyena-ctx items: XCD-contiguous channel ownership (32 adjacent channels per XCD) so the Z column stores merge in one L2; layer-0 ctx retout index arithmetic tightened (same mapping)
# speedup vs baseline: 1.0161x; 1.0028x over previous
.LBB0_17:
	s_and_b64 vcc, exec, s[84:85]
	v_writelane_b32 v253, s3, 14
	s_cbranch_vccz .LBB0_23
	s_mul_hi_u32 s0, s3, 0xaaaaaaab
	s_lshr_b32 s2, s0, 2
	s_mul_i32 s8, s2, s81
	s_add_i32 s8, s8, s88
	s_cmpk_lt_i32 s8, 0x100
	s_cselect_b64 s[0:1], -1, 0
	s_cmpk_gt_i32 s8, 0xff
	s_cbranch_scc1 .LBB0_105
	s_mul_i32 s9, s2, -6
	s_add_i32 s9, s9, s3
	s_add_i32 s9, s9, 3
	s_cmp_gt_u32 s9, 5
	s_cselect_b32 s4, 6, 0
	s_sub_i32 s9, s9, s4
	s_cmp_lt_i32 s9, 1
	s_cbranch_scc1 .LBB0_106
	s_cmp_eq_u32 s9, 1
	s_mov_b64 s[4:5], -1
	s_cbranch_scc0 .LBB0_22
	v_readlane_b32 s4, v252, 50
	s_sub_i32 s2, s8, 64
	s_lshr_b32 s5, s2, 3
	s_and_b32 s3, s8, 7
	s_lshl_b32 s3, s3, 5
	s_add_i32 s5, s5, s3
	s_cmpk_lt_u32 s2, 0xc0
	s_cselect_b32 s3, 2, -1
	s_cmp_eq_u32 s4, 0
	s_cselect_b32 s3, s3, -1
	s_cmp_eq_u32 s3, 2
	s_cselect_b32 s2, s5, 0
	s_mov_b64 s[4:5], 0

.Lg1_xb:
	s_cmpk_lt_i32 s73, 0x80
	s_cbranch_scc0 .Lg1_xc
	s_and_b32 s2, s73, 7
	s_lshl4_add_u32 s2, s2, 8
	s_lshr_b32 s3, s73, 3
	s_lshl1_add_u32 s2, s2, s3
	s_mov_b32 s3, 2
	s_branch .Lg1_xgo
.Lg1_xc:
	s_cmpk_lt_i32 s73, 0xc0
	s_cbranch_scc0 .Lg1_xnone
	s_and_b32 s4, s73, 7
	s_lshr_b32 s3, s73, 4
	s_lshl2_add_u32 s4, s4, s3
	s_mul_i32 s4, s4, 18
	s_bfe_u32 s2, s73, 0x10003
	s_add_i32 s2, s4, s2
	s_addk_i32 s2, 0xff80
	s_mov_b32 s3, 3
